# non-halo group seams: L1 invalidate issued right after the arrival atomic (overlaps the poll) instead of after it
# speedup vs baseline: 1.0169x; 1.0010x over previous
.Llb_have:
	global_atomic_add v2, v1, s[10:11]
	buffer_inv sc1
	s_mov_b32 s17, 0x300
	s_mov_b32 s15, 0
	s_mov_b32 s14, 1
	s_branch .Llb_pollsetup

.Llb_h_notlast:
	s_lshl_b32 s16, s17, 8
	s_or_b32 s13, s13, s16
	s_add_i32 s17, s14, 0x2c0
	s_mov_b32 s14, 0

.Llb_done:
	s_cmp_eq_u32 s14, 1
	s_cbranch_scc1 .LBB0_202
	buffer_inv sc1
	s_waitcnt vmcnt(0)
	s_branch .LBB0_202
